# placement experiment: G1 tile loop and later code shifted +32 B relative to v93
# baseline (speedup 1.0000x reference)
;     DI bool next(int i, Unit& u) const { if (i >= 4) return false; u.pm = pm; u.pn = i; return true; }
; #define PG8_STAGE(bufoff, gbase, voff) do { _Pragma("unroll") for (int _i = 0; _i < 2; ++_i) \
;         __builtin_amdgcn_global_load_lds((const unsigned*)((const char*)(gbase) + (voff)[_i]), (LAS unsigned*)(lds + (bufoff) + ldsw + _i * 8192), 16, 0, 0); } while (0)
; #define PG8_WAIT_V(n) asm volatile("s_waitcnt vmcnt(" #n ")" ::: "memory")
; #define PG8_BAR __builtin_amdgcn_s_barrier()
;     DI bool next(int i, Unit& u) const {
;         const long L = (long)i * G + c; if (L >= nwg) return false;
;         int wgid = (int)L; { const int q = nwg / NXCD, r = nwg % NXCD, xcd = wgid % NXCD, off = wgid / NXCD; wgid = (xcd < r ? xcd * (q + 1) : r * (q + 1) + (xcd - r) * q) + off; }
;         const int nig = WGM * nN, gid = wgid / nig, fm = gid * WGM, gsz = (nM - fm) < WGM ? (nM - fm) : WGM;
;         u.pm = fm + ((wgid % nig) % gsz); u.pn = (wgid % nig) / gsz; return true;
; template <class Epi, class Sched>
; DI void gemm_phase(ldsp lds, const Gemm g, const Sched& S, const Epi& E, const int tid) {
;     ...
;     PG8_STAGE(PG8_SB(0, 0), cB, voffB); PG8_STAGE(PG8_SA(0, 0), cA, voffA); PG8_STAGE(PG8_SB(0, 1), cB + hstep, voffB); PG8_STAGE(PG8_SA(0, 1), cA + hstep, voffA);
;     if (wr == 1) PG8_BAR;
;     PG8_WAIT_V(4); PG8_BAR;
;     PG8_STAGE(PG8_SB(1, 0), cB + kstep, voffB); PG8_STAGE(PG8_SA(1, 0), cA + kstep, voffA); PG8_STAGE(PG8_SB(1, 1), cB + hstep + kstep, voffB);
;     PG8_WAIT_V(6); PG8_BAR;
;     for (;;) {
;         const bool has_next = S.next(ui + 1, nxt);
.LBB0_659:
	s_sext_i32_i16 s64, s26
	v_readlane_b32 s26, v255, 9
	s_lshl_b32 s26, s26, 27
	s_and_b32 s38, s26, 0x8000000
	s_and_b64 s[26:27], s[42:43], exec
	s_cselect_b32 s26, 0, s38
	s_lshl_b32 s26, s26, 1
	v_readlane_b32 s38, v251, 15
	v_readlane_b32 s39, v251, 16
	s_add_u32 s26, s38, s26
	v_lshrrev_b32_e32 v16, 1, v32
	s_addc_u32 s27, s39, 0
	v_and_b32_e32 v16, 24, v16
	s_lshl_b32 s36, s36, 5
	v_lshlrev_b32_e32 v17, 1, v16
	v_lshlrev_b32_e32 v18, 2, v155
	s_and_b32 s38, s36, 0x60
	s_add_i32 m0, s31, 0x18000
	v_lshl_add_u64 v[6:7], v[6:7], 0, s[96:97]
	v_lshl_or_b32 v13, s37, 6, v155
	v_lshl_or_b32 v17, v155, 6, v17
	s_lshl_b32 s37, s37, 13
	v_and_b32_e32 v18, 32, v18
	s_lshl_b32 s36, s38, 7
	s_waitcnt vmcnt(4)
	s_barrier
	global_load_lds_dwordx4 v[6:7], off
	v_lshl_add_u64 v[4:5], v[4:5], 0, s[96:97]
	s_add_i32 m0, s31, 0x1a000
	s_add_i32 s62, s31, 0x8000
	s_add_i32 s63, s31, 0xa000
	v_bitop3_b32 v33, s36, v17, v18 bitop3:0xf6
	global_load_lds_dwordx4 v[4:5], off
	v_lshl_add_u64 v[2:3], v[2:3], 0, s[96:97]
	s_mov_b32 m0, s62
	s_add_u32 s36, s48, 0x40080
	v_bitop3_b32 v19, v17, s37, v18 bitop3:0xde
	global_load_lds_dwordx4 v[2:3], off
	v_lshl_add_u64 v[0:1], v[0:1], 0, s[96:97]
	s_mov_b32 m0, s63
	s_addc_u32 s37, s49, 0
	global_load_lds_dwordx4 v[0:1], off
	s_add_i32 m0, s31, 0x1c000
	v_lshl_add_u64 v[0:1], s[36:37], 0, v[136:137]
	global_load_lds_dwordx4 v[0:1], off
	v_lshl_add_u64 v[0:1], s[36:37], 0, v[30:31]
	s_add_i32 m0, s31, 0x1e000
	s_mov_b32 s61, 0
	global_load_lds_dwordx4 v[0:1], off
	v_lshlrev_b32_e32 v0, 14, v14
	v_and_b32_e32 v0, 0xffff8000, v0
	v_lshl_add_u32 v0, v11, 11, v0
	v_and_b32_e32 v1, 1, v14
	v_lshl_or_b32 v0, v1, 6, v0
	v_lshl_add_u32 v140, v15, 1, v0
	v_lshlrev_b32_e32 v0, 14, v8
	v_and_b32_e32 v0, 0xffff8000, v0
	s_waitcnt vmcnt(6)
	v_lshl_add_u32 v0, v9, 11, v0
	v_and_b32_e32 v1, 1, v8
	v_lshl_or_b32 v0, v1, 6, v0
	v_or_b32_e32 v144, s38, v16
	v_mov_b32_e32 v141, v12
	v_lshl_add_u32 v142, v10, 1, v0
	v_mov_b32_e32 v143, v12
	v_add_u32_e32 v145, 0, v19
	s_barrier
	v_mul_lo_u32 v224, v13, s14
	v_add_lshl_u32 v224, v224, v144, 1
	s_lshl_b32 s100, s14, 5
	s_nop 0
	s_nop 0
	s_nop 0
	s_nop 0
	s_nop 0
	s_nop 0
	s_nop 0
	s_nop 0
.LBB0_660:
	s_add_i32 s61, s61, 1
	v_readlane_b32 s37, v251, 42
	s_mul_i32 s37, s61, s37
	s_mul_hi_u32 s38, s61, s10
	s_add_i32 s38, s38, s37
	s_mul_i32 s37, s61, s10
	s_add_u32 s42, s37, s78
	v_readlane_b32 s37, v251, 41
	s_addc_u32 s43, s38, s37
	v_mov_b64_e32 v[0:1], s[0:1]
	v_cmp_ge_i64_e64 s[38:39], s[42:43], v[0:1]
	s_and_b64 vcc, exec, s[38:39]
	s_cbranch_vccnz .LBB0_662
	s_ashr_i32 s36, s42, 31
	s_lshr_b32 s36, s36, 29
	s_add_i32 s36, s42, s36
	s_ashr_i32 s37, s36, 3
	s_and_b32 s36, s36, -8
	s_sub_i32 s36, s42, s36
	s_cmp_lt_i32 s36, 0
	s_cselect_b32 s40, s53, s52
	s_mul_i32 s36, s40, s36
	s_add_i32 s36, s36, s37
	s_abs_i32 s40, s36
	s_mul_hi_u32 s41, s40, s57
	s_mul_i32 s44, s41, s55
	s_ashr_i32 s37, s36, 31
	s_sub_i32 s40, s40, s44
	s_xor_b32 s37, s37, s56
	s_add_i32 s44, s41, 1
	s_sub_i32 s45, s40, s55
	s_cmp_ge_u32 s40, s55
	s_cselect_b32 s41, s44, s41
	s_cselect_b32 s40, s45, s40
	s_add_i32 s44, s41, 1
	s_cmp_ge_u32 s40, s55
	s_cselect_b32 s40, s44, s41
	s_xor_b32 s40, s40, s37
	s_sub_i32 s37, s40, s37
	s_lshl_b32 s40, s37, 3
	s_sub_i32 s41, s34, s40
	s_min_i32 s41, s41, 8
	s_abs_i32 s44, s41
	v_cvt_f32_u32_e32 v0, s44
	s_sub_i32 s50, 0, s44
	s_mul_i32 s37, s37, s54
	s_sub_i32 s37, s36, s37
	v_rcp_iflag_f32_e32 v0, v0
	s_abs_i32 s45, s37
	s_xor_b32 s36, s37, s41
	s_ashr_i32 s36, s36, 31
	v_mul_f32_e32 v0, 0x4f7ffffe, v0
	v_cvt_u32_f32_e32 v0, v0
	s_nop 0
	v_readfirstlane_b32 s51, v0
	s_mul_i32 s50, s50, s51
	s_mul_hi_u32 s50, s51, s50
	s_add_i32 s51, s51, s50
	s_mul_hi_u32 s50, s45, s51
	s_mul_i32 s51, s50, s44
	s_sub_i32 s45, s45, s51
	s_add_i32 s51, s50, 1
	s_sub_i32 s65, s45, s44
	s_cmp_ge_u32 s45, s44
	s_cselect_b32 s50, s51, s50
	s_cselect_b32 s45, s65, s45
	s_add_i32 s51, s50, 1
	s_cmp_ge_u32 s45, s44
	s_cselect_b32 s44, s51, s50
	s_xor_b32 s44, s44, s36
	s_sub_i32 s36, s44, s36
	s_mul_i32 s41, s36, s41
	s_sub_i32 s37, s37, s41
	s_add_i32 s40, s37, s40
